# grid barrier: L1 invalidate (buffer_inv sc1) moved off lane 0's protocol path to wave 1, issued at barrier entry concurrently with arrive/poll (12 of 15 barrier copies)
# speedup vs baseline: 1.0070x; 1.0028x over previous
; __device__ __forceinline__ unsigned xb_ld(unsigned* p)              { return __hip_atomic_load(p, __ATOMIC_RELAXED, __HIP_MEMORY_SCOPE_AGENT); }
; __device__ __forceinline__ unsigned xb_add(unsigned* p, unsigned v) { return __hip_atomic_fetch_add(p, v, __ATOMIC_RELAXED, __HIP_MEMORY_SCOPE_AGENT); }
; #define XB_SPIN(cond, bar) do { unsigned _sp = 0; while (cond) { __builtin_amdgcn_s_sleep(1); \
;     if ((++_sp & 255u) == 0u) { if (xb_ld(&(bar)[XB_TMO])) break; if (_sp > XB_SPIN_CAP) { atomicAdd(&(bar)[XB_TMO], 1u); break; } } } } while (0)
; __device__ __forceinline__ void xcd_barrier(const XcdBarrier& b) {
;     asm volatile("s_waitcnt vmcnt(0)" ::: "memory");
;     __syncthreads();
;     if (threadIdx.x == 0) {
;         unsigned* bar = b.bar;
;         __builtin_amdgcn_s_waitcnt(0);
;         unsigned nloc = b.st[0], nx = b.st[1];
;         if (nloc == 0u) { xcd_barrier_complete(bar, b.x, nloc, nx); b.st[0] = nloc; b.st[1] = nx; }
;         const unsigned old = xb_add(&bar[XB_XSUB(b.x)], 1u);
;         const unsigned gen = old / nloc;
;         if (old + 1u == (gen + 1u) * nloc) {
;             __builtin_amdgcn_fence(__ATOMIC_RELEASE, "agent");
;             asm volatile("s_waitcnt vmcnt(0)" ::: "memory");
;             const unsigned og = xb_add(&bar[XB_TOP], 1u);
;             const unsigned tg = og / nx;
;             if (og + 1u == (tg + 1u) * nx) xb_add(&bar[XB_TOPGEN], 1u);
;             else XB_SPIN(xb_ld(&bar[XB_TOPGEN]) == tg, bar);
;             __builtin_amdgcn_fence(__ATOMIC_ACQUIRE, "agent");
;             xb_add(&bar[XB_XGEN(b.x)], 1u);
;             asm volatile("s_waitcnt vmcnt(0)" ::: "memory");
.LBB0_148:
	s_or_b64 exec, exec, s[8:9]
	v_mov_b32_e32 v1, 0x2000
	v_mov_b32_e32 v2, 1
	s_waitcnt vmcnt(0)
	global_atomic_add v1, v2, s[6:7] offset:1024
	s_waitcnt vmcnt(0)
	s_branch .LBB0_149
.Lbinv_0:
	s_or_b64 exec, exec, s[4:5]
	v_readfirstlane_b32 s6, v0
	s_lshr_b32 s6, s6, 6
	s_cmp_lg_u32 s6, 1
	s_cbranch_scc1 .LBB0_149
	buffer_inv sc1
	s_waitcnt vmcnt(0)

; __device__ __forceinline__ unsigned xb_ld(unsigned* p)              { return __hip_atomic_load(p, __ATOMIC_RELAXED, __HIP_MEMORY_SCOPE_AGENT); }
; __device__ __forceinline__ unsigned xb_add(unsigned* p, unsigned v) { return __hip_atomic_fetch_add(p, v, __ATOMIC_RELAXED, __HIP_MEMORY_SCOPE_AGENT); }
; #define XB_SPIN(cond, bar) do { unsigned _sp = 0; while (cond) { __builtin_amdgcn_s_sleep(1); \
;     if ((++_sp & 255u) == 0u) { if (xb_ld(&(bar)[XB_TMO])) break; if (_sp > XB_SPIN_CAP) { atomicAdd(&(bar)[XB_TMO], 1u); break; } } } } while (0)
; __device__ __forceinline__ void xcd_barrier(const XcdBarrier& b) {
;     asm volatile("s_waitcnt vmcnt(0)" ::: "memory");
;     __syncthreads();
;     if (threadIdx.x == 0) {
;         unsigned* bar = b.bar;
;         __builtin_amdgcn_s_waitcnt(0);
;         unsigned nloc = b.st[0], nx = b.st[1];
;         if (nloc == 0u) { xcd_barrier_complete(bar, b.x, nloc, nx); b.st[0] = nloc; b.st[1] = nx; }
;         const unsigned old = xb_add(&bar[XB_XSUB(b.x)], 1u);
;         const unsigned gen = old / nloc;
;         if (old + 1u == (gen + 1u) * nloc) {
;             __builtin_amdgcn_fence(__ATOMIC_RELEASE, "agent");
;             asm volatile("s_waitcnt vmcnt(0)" ::: "memory");
;             const unsigned og = xb_add(&bar[XB_TOP], 1u);
;             const unsigned tg = og / nx;
;             if (og + 1u == (tg + 1u) * nx) xb_add(&bar[XB_TOPGEN], 1u);
;             else XB_SPIN(xb_ld(&bar[XB_TOPGEN]) == tg, bar);
;             __builtin_amdgcn_fence(__ATOMIC_ACQUIRE, "agent");
;             xb_add(&bar[XB_XGEN(b.x)], 1u);
;             asm volatile("s_waitcnt vmcnt(0)" ::: "memory");
.LBB0_220:
	s_or_b64 exec, exec, s[6:7]
	v_mov_b32_e32 v1, 0x2000
	v_mov_b32_e32 v2, 1
	s_waitcnt vmcnt(0)
	global_atomic_add v1, v2, s[4:5] offset:1024
	s_waitcnt vmcnt(0)
	s_branch .LBB0_221
.Lbinv_1:
	s_or_b64 exec, exec, s[0:1]
	v_readfirstlane_b32 s4, v0
	s_lshr_b32 s4, s4, 6
	s_cmp_lg_u32 s4, 1
	s_cbranch_scc1 .LBB0_221
	buffer_inv sc1
	s_waitcnt vmcnt(0)

; __device__ __forceinline__ unsigned xb_ld(unsigned* p)              { return __hip_atomic_load(p, __ATOMIC_RELAXED, __HIP_MEMORY_SCOPE_AGENT); }
; __device__ __forceinline__ unsigned xb_add(unsigned* p, unsigned v) { return __hip_atomic_fetch_add(p, v, __ATOMIC_RELAXED, __HIP_MEMORY_SCOPE_AGENT); }
; #define XB_SPIN(cond, bar) do { unsigned _sp = 0; while (cond) { __builtin_amdgcn_s_sleep(1); \
;     if ((++_sp & 255u) == 0u) { if (xb_ld(&(bar)[XB_TMO])) break; if (_sp > XB_SPIN_CAP) { atomicAdd(&(bar)[XB_TMO], 1u); break; } } } } while (0)
; __device__ __forceinline__ void xcd_barrier(const XcdBarrier& b) {
;     asm volatile("s_waitcnt vmcnt(0)" ::: "memory");
;     __syncthreads();
;     if (threadIdx.x == 0) {
;         unsigned* bar = b.bar;
;         __builtin_amdgcn_s_waitcnt(0);
;         unsigned nloc = b.st[0], nx = b.st[1];
;         if (nloc == 0u) { xcd_barrier_complete(bar, b.x, nloc, nx); b.st[0] = nloc; b.st[1] = nx; }
;         const unsigned old = xb_add(&bar[XB_XSUB(b.x)], 1u);
;         const unsigned gen = old / nloc;
;         if (old + 1u == (gen + 1u) * nloc) {
;             __builtin_amdgcn_fence(__ATOMIC_RELEASE, "agent");
;             asm volatile("s_waitcnt vmcnt(0)" ::: "memory");
;             const unsigned og = xb_add(&bar[XB_TOP], 1u);
;             const unsigned tg = og / nx;
;             if (og + 1u == (tg + 1u) * nx) xb_add(&bar[XB_TOPGEN], 1u);
;             else XB_SPIN(xb_ld(&bar[XB_TOPGEN]) == tg, bar);
;             __builtin_amdgcn_fence(__ATOMIC_ACQUIRE, "agent");
;             xb_add(&bar[XB_XGEN(b.x)], 1u);
;             asm volatile("s_waitcnt vmcnt(0)" ::: "memory");
.LBB0_328:
	s_or_b64 exec, exec, s[4:5]
	v_readlane_b32 s4, v253, 59
	v_readlane_b32 s5, v253, 60
	s_waitcnt vmcnt(0)
	s_nop 2
	global_atomic_add v3, v1, s[4:5]
	s_waitcnt vmcnt(0)
	s_branch .LBB0_329
.Lbinv_2:
	s_or_b64 exec, exec, s[0:1]
	v_readfirstlane_b32 s6, v0
	s_lshr_b32 s6, s6, 6
	s_cmp_lg_u32 s6, 1
	s_cbranch_scc1 .LBB0_329
	buffer_inv sc1
	s_waitcnt vmcnt(0)

; __device__ __forceinline__ unsigned xb_ld(unsigned* p)              { return __hip_atomic_load(p, __ATOMIC_RELAXED, __HIP_MEMORY_SCOPE_AGENT); }
; __device__ __forceinline__ unsigned xb_add(unsigned* p, unsigned v) { return __hip_atomic_fetch_add(p, v, __ATOMIC_RELAXED, __HIP_MEMORY_SCOPE_AGENT); }
; #define XB_SPIN(cond, bar) do { unsigned _sp = 0; while (cond) { __builtin_amdgcn_s_sleep(1); \
;     if ((++_sp & 255u) == 0u) { if (xb_ld(&(bar)[XB_TMO])) break; if (_sp > XB_SPIN_CAP) { atomicAdd(&(bar)[XB_TMO], 1u); break; } } } } while (0)
; __device__ __forceinline__ void xcd_barrier(const XcdBarrier& b) {
;     asm volatile("s_waitcnt vmcnt(0)" ::: "memory");
;     __syncthreads();
;     if (threadIdx.x == 0) {
;         unsigned* bar = b.bar;
;         __builtin_amdgcn_s_waitcnt(0);
;         unsigned nloc = b.st[0], nx = b.st[1];
;         if (nloc == 0u) { xcd_barrier_complete(bar, b.x, nloc, nx); b.st[0] = nloc; b.st[1] = nx; }
;         const unsigned old = xb_add(&bar[XB_XSUB(b.x)], 1u);
;         const unsigned gen = old / nloc;
;         if (old + 1u == (gen + 1u) * nloc) {
;             __builtin_amdgcn_fence(__ATOMIC_RELEASE, "agent");
;             asm volatile("s_waitcnt vmcnt(0)" ::: "memory");
;             const unsigned og = xb_add(&bar[XB_TOP], 1u);
;             const unsigned tg = og / nx;
;             if (og + 1u == (tg + 1u) * nx) xb_add(&bar[XB_TOPGEN], 1u);
;             else XB_SPIN(xb_ld(&bar[XB_TOPGEN]) == tg, bar);
;             __builtin_amdgcn_fence(__ATOMIC_ACQUIRE, "agent");
;             xb_add(&bar[XB_XGEN(b.x)], 1u);
;             asm volatile("s_waitcnt vmcnt(0)" ::: "memory");
.Lbinv_4:
	s_or_b64 exec, exec, s[0:1]
	v_readfirstlane_b32 s8, v0
	s_lshr_b32 s8, s8, 6
	s_cmp_lg_u32 s8, 1
	s_cbranch_scc1 .LBB0_510
	buffer_inv sc1
	s_waitcnt vmcnt(0)
